# v59 + MLA loop: first QK MFMA of each half issued before the DMA block (and before the 8 v_fma in half 1)
# baseline (speedup 1.0000x reference)
.LBB0_543:
	s_mov_b32 s23, s17
	s_mov_b32 s17, s0
	s_add_i32 s71, 0, 0x10000
	ds_read_b128 v[66:69], v174 offset:49152
	ds_read_b128 v[70:73], v174 offset:57344
	ds_read_b128 v[206:209], v176 offset:49152
	ds_read_b128 v[210:213], v176 offset:57344
	v_exp_f32_e32 v229, v229
	v_exp_f32_e32 v231, v231
	v_exp_f32_e32 v227, v227
	v_exp_f32_e32 v230, v230
	v_exp_f32_e32 v226, v226
	v_exp_f32_e32 v228, v228
	s_waitcnt lgkmcnt(3)
	v_mfma_f32_32x32x16_bf16 v[82:97], v[66:69], v[142:145], 0
	s_add_u32 s4, s38, s20
	s_addc_u32 s5, s39, s21
	s_add_u32 s24, s4, 0x149ec400
	s_addc_u32 s25, s5, 0
	s_mov_b32 m0, s90
	v_lshl_add_u64 v[254:255], v[246:247], 0, s[24:25]
	s_lshl_b32 s18, s22, 14
	global_load_lds_dwordx4 v[254:255], off
	s_add_u32 s24, s4, 0x14a0c400
	s_addc_u32 s25, s5, 0
	s_mov_b32 m0, s91
	v_lshl_add_u64 v[254:255], v[246:247], 0, s[24:25]
	s_add_i32 s1, s89, s18
	global_load_lds_dwordx4 v[254:255], off
	s_add_u32 s24, s4, 0x149ec500
	s_addc_u32 s25, s5, 0
	s_mov_b32 m0, s1
	v_lshl_add_u64 v[254:255], v[248:249], 0, s[24:25]
	global_load_lds_dwordx4 v[254:255], off
	s_add_u32 s24, s4, 0x14a0c500
	s_addc_u32 s25, s5, 0
	s_add_i32 m0, s1, 0x2000
	v_lshl_add_u64 v[254:255], v[248:249], 0, s[24:25]
	global_load_lds_dwordx4 v[254:255], off
	s_add_u32 s4, s38, s88
	s_addc_u32 s5, s39, s87
	s_add_u32 s4, s4, s36
	s_addc_u32 s5, s5, s37
	s_mov_b32 m0, s92
	v_lshl_add_u64 v[254:255], v[250:251], 0, s[4:5]
	global_load_lds_dwordx4 v[254:255], off
	v_fma_f32 v152, v74, s34, v146
	v_fma_f32 v153, v75, s34, v146
	v_fma_f32 v150, v76, s34, v146
	v_fma_f32 v151, v77, s34, v146
	v_fma_f32 v148, v78, s34, v146
	v_fma_f32 v149, v79, s34, v146
	v_fma_f32 v147, v81, s34, v146
	v_fma_f32 v146, v80, s34, v146
	s_add_i32 s0, 0, 0x16000
	v_exp_f32_e32 v240, v146
	v_add_f32_e32 v146, 0, v229
	v_add_f32_e32 v146, v231, v146
	v_add_f32_e32 v146, v227, v146
	v_add_f32_e32 v146, v230, v146
	v_add_f32_e32 v146, v226, v146
	v_exp_f32_e32 v224, v224
	v_exp_f32_e32 v225, v225
	v_exp_f32_e32 v221, v221
	v_exp_f32_e32 v223, v223
	s_waitcnt lgkmcnt(0)
	v_mfma_f32_32x32x16_bf16 v[66:81], v[70:73], v[142:145], 0
	v_exp_f32_e32 v220, v220
	v_exp_f32_e32 v222, v222
	v_add_f32_e32 v146, v228, v146
	v_add_f32_e32 v146, v224, v146
	v_add_f32_e32 v146, v225, v146
	v_add_f32_e32 v146, v221, v146
	v_add_f32_e32 v146, v223, v146
	v_add_f32_e32 v146, v220, v146
	v_add_f32_e32 v146, v222, v146
	v_exp_f32_e32 v217, v217
	v_exp_f32_e32 v219, v219
	v_exp_f32_e32 v216, v216
	v_exp_f32_e32 v218, v218
	v_mfma_f32_32x32x16_bf16 v[82:97], v[206:209], v[138:141], v[82:97]
	v_exp_f32_e32 v164, v164
	v_add_f32_e32 v146, v217, v146
	v_exp_f32_e32 v165, v165
	v_add_f32_e32 v146, v219, v146
	v_exp_f32_e32 v197, v162
	v_add_f32_e32 v146, v216, v146
	v_add_f32_e32 v146, v218, v146
	v_mfma_f32_32x32x16_bf16 v[66:81], v[210:213], v[138:141], v[66:81]
	ds_read_b128 v[206:209], v178 offset:49152
	ds_read_b128 v[210:213], v178 offset:57344
	v_exp_f32_e32 v156, v156
	v_add_f32_e32 v146, v164, v146
	v_exp_f32_e32 v157, v157
	v_add_f32_e32 v146, v165, v146
	v_add_f32_e32 v146, v197, v146
	v_exp_f32_e32 v241, v147
	s_waitcnt lgkmcnt(0)
	v_mfma_f32_32x32x16_bf16 v[82:97], v[206:209], v[134:137], v[82:97]
	v_mfma_f32_32x32x16_bf16 v[66:81], v[210:213], v[134:137], v[66:81]
	ds_read_b128 v[208:211], v180 offset:49152
	ds_read_b128 v[212:215], v180 offset:57344
	s_waitcnt lgkmcnt(0)
	v_mfma_f32_32x32x16_bf16 v[82:97], v[208:211], v[130:133], v[82:97]
	v_mfma_f32_32x32x16_bf16 v[66:81], v[212:215], v[130:133], v[66:81]
	ds_read_b128 v[208:211], v182 offset:49152
	ds_read_b128 v[212:215], v182 offset:57344
	s_waitcnt lgkmcnt(0)
	v_mfma_f32_32x32x16_bf16 v[82:97], v[208:211], v[126:129], v[82:97]
	v_mfma_f32_32x32x16_bf16 v[66:81], v[212:215], v[126:129], v[66:81]
	ds_read_b128 v[210:213], v186 offset:49152
	ds_read_b128 v[232:235], v186 offset:57344
	s_waitcnt lgkmcnt(0)
	v_mfma_f32_32x32x16_bf16 v[82:97], v[210:213], v[122:125], v[82:97]
	v_mfma_f32_32x32x16_bf16 v[66:81], v[232:235], v[122:125], v[66:81]
	ds_read_b128 v[210:213], v188 offset:49152
	ds_read_b128 v[232:235], v188 offset:57344
	s_waitcnt lgkmcnt(0)
	v_mfma_f32_32x32x16_bf16 v[82:97], v[210:213], v[118:121], v[82:97]
	v_mfma_f32_32x32x16_bf16 v[66:81], v[232:235], v[118:121], v[66:81]
	ds_read_b128 v[212:215], v190 offset:49152
	ds_read_b128 v[232:235], v190 offset:57344
	s_waitcnt lgkmcnt(0)
	v_mfma_f32_32x32x16_bf16 v[82:97], v[212:215], v[114:117], v[82:97]
	v_mfma_f32_32x32x16_bf16 v[66:81], v[232:235], v[114:117], v[66:81]
	ds_read_b128 v[212:215], v192 offset:8192
	ds_read_b128 v[232:235], v192 offset:12288
	s_waitcnt lgkmcnt(0)
	v_mfma_f32_32x32x16_bf16 v[82:97], v[212:215], v[110:113], v[82:97]
	v_exp_f32_e32 v215, v163
	s_nop 0
	v_add_f32_e32 v146, v215, v146
	v_mfma_f32_32x32x16_bf16 v[66:81], v[232:235], v[110:113], v[66:81]
	s_lshl_b32 s24, s17, 14
	v_add_u32_e32 v245, s24, v200
	ds_read_b64_tr_b16 v[206:207], v245 offset:0
	ds_read_b64_tr_b16 v[208:209], v245 offset:0x800
	ds_read_b64_tr_b16 v[210:211], v245 offset:0x1000
	ds_read_b64_tr_b16 v[212:213], v245 offset:0x1800
	ds_read_b128 v[232:235], v194 offset:8192
	ds_read_b128 v[236:239], v194 offset:12288
	v_add_f32_e32 v146, v156, v146
	v_add_f32_e32 v146, v157, v146
	s_waitcnt lgkmcnt(0)
	v_mfma_f32_32x32x16_bf16 v[82:97], v[232:235], v[106:109], v[82:97]
	v_mfma_f32_32x32x16_bf16 v[66:81], v[236:239], v[106:109], v[66:81]
	ds_read_b128 v[232:235], v196 offset:8192
	ds_read_b128 v[236:239], v196 offset:12288
	s_waitcnt lgkmcnt(0)
	v_mfma_f32_32x32x16_bf16 v[82:97], v[232:235], v[102:105], v[82:97]
	v_mfma_f32_32x32x16_bf16 v[66:81], v[236:239], v[102:105], v[66:81]
	ds_read_b128 v[232:235], v199 offset:8192
	ds_read_b128 v[236:239], v199 offset:12288
	s_waitcnt lgkmcnt(0)
	v_mfma_f32_32x32x16_bf16 v[82:97], v[232:235], v[98:101], v[82:97]
	v_exp_f32_e32 v232, v154
	v_exp_f32_e32 v233, v155
	v_exp_f32_e32 v234, v152
	v_exp_f32_e32 v235, v153
	v_add_f32_e32 v146, v232, v146
	v_add_f32_e32 v146, v233, v146
	v_add_f32_e32 v146, v234, v146
	v_mfma_f32_32x32x16_bf16 v[66:81], v[236:239], v[98:101], v[66:81]
	v_exp_f32_e32 v236, v150
	v_exp_f32_e32 v237, v151
	v_exp_f32_e32 v238, v148
	v_exp_f32_e32 v239, v149
	v_add_f32_e32 v146, v235, v146
	v_add_f32_e32 v146, v236, v146
	v_add_f32_e32 v146, v237, v146
	v_add_f32_e32 v146, v238, v146
	v_add_f32_e32 v146, v239, v146
	v_add_f32_e32 v146, v240, v146
	v_add_f32_e32 v162, v241, v146
	v_mov_b32_e32 v163, v162
	s_nop 1
	v_permlane32_swap_b32_e32 v162, v163
	v_cvt_pk_bf16_f32 v146, v229, v231
	v_cvt_pk_bf16_f32 v147, v227, v230
	v_cvt_pk_bf16_f32 v148, v226, v228
	v_cvt_pk_bf16_f32 v149, v224, v225
	v_cvt_pk_bf16_f32 v150, v221, v223
	v_cvt_pk_bf16_f32 v151, v220, v222
	v_cvt_pk_bf16_f32 v152, v217, v219
	v_cvt_pk_bf16_f32 v153, v216, v218
	v_cvt_pk_bf16_f32 v154, v164, v165
	v_cvt_pk_bf16_f32 v155, v197, v215
	v_cvt_pk_bf16_f32 v156, v156, v157
	v_cvt_pk_bf16_f32 v157, v232, v233
	v_cvt_pk_bf16_f32 v216, v234, v235
	v_cvt_pk_bf16_f32 v217, v236, v237
	v_cvt_pk_bf16_f32 v218, v238, v239
	v_cvt_pk_bf16_f32 v219, v240, v241
	s_nop 0
	v_permlane32_swap_b32_e32 v146, v148
	v_permlane32_swap_b32_e32 v147, v149
	v_permlane32_swap_b32_e32 v150, v152
	v_permlane32_swap_b32_e32 v151, v153
	v_permlane32_swap_b32_e32 v154, v156
	v_permlane32_swap_b32_e32 v155, v157
	v_permlane32_swap_b32_e32 v216, v218
	v_permlane32_swap_b32_e32 v217, v219
	s_lshl_b32 s24, s17, 14
	v_add_u32_e32 v197, s24, v200
	ds_read_b64_tr_b16 v[228:229], v197 offset:0x2000
	ds_read_b64_tr_b16 v[230:231], v197 offset:0x2800
	ds_read_b64_tr_b16 v[232:233], v197 offset:0x3000
	ds_read_b64_tr_b16 v[234:235], v197 offset:0x3800
	s_nop 0
	v_mfma_f32_32x32x16_bf16 v[2:17], v[146:149], v[206:209], v[2:17]
	ds_read_b64_tr_b16 v[220:221], v197 offset:0x200
	ds_read_b64_tr_b16 v[222:223], v197 offset:0xa00
	v_max_f32_e32 v164, v83, v83
	v_max_f32_e32 v165, v82, v82
	v_max_f32_e32 v164, v165, v164
	v_max3_f32 v164, v164, v84, v85
	v_max3_f32 v164, v164, v86, v87
	v_mfma_f32_32x32x16_bf16 v[2:17], v[150:153], v[210:213], v[2:17]
	ds_read_b64_tr_b16 v[224:225], v197 offset:0x1200
	ds_read_b64_tr_b16 v[226:227], v197 offset:0x1a00
	v_max3_f32 v164, v164, v88, v89
	v_max3_f32 v164, v164, v90, v91
	v_max3_f32 v164, v164, v92, v93
	v_max3_f32 v164, v164, v94, v95
	v_max3_f32 v164, v164, v96, v97
	s_waitcnt lgkmcnt(6)
	v_mfma_f32_32x32x16_bf16 v[2:17], v[154:157], v[228:231], v[2:17]
	ds_read_b64_tr_b16 v[228:229], v197 offset:0x2200
	ds_read_b64_tr_b16 v[230:231], v197 offset:0x2a00
	ds_read_b64_tr_b16 v[236:237], v197 offset:0x3200
	ds_read_b64_tr_b16 v[238:239], v197 offset:0x3a00
	s_waitcnt lgkmcnt(8)
	v_mfma_f32_32x32x16_bf16 v[2:17], v[216:219], v[232:235], v[2:17]
	s_waitcnt lgkmcnt(6)
	v_mfma_f32_32x32x16_bf16 v[50:65], v[146:149], v[220:223], v[50:65]
	v_max3_f32 v164, v164, v66, v67
	v_max3_f32 v164, v164, v68, v69
	v_max3_f32 v164, v164, v70, v71
	v_max3_f32 v164, v164, v72, v73
	v_max3_f32 v164, v164, v74, v75
	v_max3_f32 v164, v164, v76, v77
	v_max3_f32 v164, v164, v78, v79
	s_waitcnt lgkmcnt(4)
	v_mfma_f32_32x32x16_bf16 v[50:65], v[150:153], v[224:227], v[50:65]
	v_max3_f32 v164, v164, v80, v81
	v_mov_b32_e32 v165, v164
	s_nop 1
	v_permlane32_swap_b32_e32 v164, v165
	ds_read_b64_tr_b16 v[220:221], v197 offset:0x400
	v_max_f32_e32 v165, v165, v165
	v_max_f32_e32 v164, v164, v164
	s_waitcnt lgkmcnt(3)
	v_mfma_f32_32x32x16_bf16 v[50:65], v[154:157], v[228:231], v[50:65]
	ds_read_b64_tr_b16 v[222:223], v197 offset:0xc00
	v_max_f32_e32 v164, v164, v165
	v_max_f32_e32 v165, v202, v202
	ds_read_b64_tr_b16 v[224:225], v197 offset:0x1400
	v_max_f32_e32 v165, v165, v164
	ds_read_b64_tr_b16 v[226:227], v197 offset:0x1c00
	v_sub_f32_e32 v215, v164, v202
	s_waitcnt lgkmcnt(4)
	v_mfma_f32_32x32x16_bf16 v[50:65], v[216:219], v[236:239], v[50:65]
	v_sub_f32_e32 v164, v202, v165
	ds_read_b64_tr_b16 v[228:229], v197 offset:0x2400
	v_mul_f32_e32 v164, 0x3dd53b94, v164
	ds_read_b64_tr_b16 v[230:231], v197 offset:0x2c00
	v_exp_f32_e32 v164, v164
	ds_read_b64_tr_b16 v[232:233], v197 offset:0x3400
	v_cmp_ge_f32_e32 vcc, s77, v215
	ds_read_b64_tr_b16 v[234:235], v197 offset:0x3c00
	s_cmp_eq_u64 vcc, exec
	s_cselect_b64 s[4:5], -1, 0
	v_cndmask_b32_e64 v164, v164, 1.0, s[4:5]
	s_waitcnt lgkmcnt(6)
	v_mfma_f32_32x32x16_bf16 v[34:49], v[146:149], v[220:223], v[34:49]
	ds_read_b64_tr_b16 v[220:221], v197 offset:0x600
	ds_read_b64_tr_b16 v[222:223], v197 offset:0xe00
	s_waitcnt lgkmcnt(6)
	v_mfma_f32_32x32x16_bf16 v[34:49], v[150:153], v[224:227], v[34:49]
	ds_read_b64_tr_b16 v[224:225], v197 offset:0x1600
	ds_read_b64_tr_b16 v[226:227], v197 offset:0x1e00
	s_waitcnt lgkmcnt(6)
	v_mfma_f32_32x32x16_bf16 v[34:49], v[154:157], v[228:231], v[34:49]
	ds_read_b64_tr_b16 v[228:229], v197 offset:0x2600
	ds_read_b64_tr_b16 v[230:231], v197 offset:0x2e00
	ds_read_b64_tr_b16 v[236:237], v197 offset:0x3600
	ds_read_b64_tr_b16 v[238:239], v197 offset:0x3e00
	s_waitcnt lgkmcnt(8)
	v_mfma_f32_32x32x16_bf16 v[34:49], v[216:219], v[232:235], v[34:49]
	s_waitcnt lgkmcnt(6)
	v_mfma_f32_32x32x16_bf16 v[18:33], v[146:149], v[220:223], v[18:33]
	v_cmp_gt_f32_e32 vcc, 1.0, v164
	s_waitcnt lgkmcnt(4)
	v_mfma_f32_32x32x16_bf16 v[18:33], v[150:153], v[224:227], v[18:33]
	s_waitcnt lgkmcnt(2)
	v_mfma_f32_32x32x16_bf16 v[18:33], v[154:157], v[228:231], v[18:33]
	s_waitcnt lgkmcnt(0)
	v_mfma_f32_32x32x16_bf16 v[18:33], v[216:219], v[236:239], v[18:33]
	s_cbranch_vccz .LBB0_547
	s_and_saveexec_b64 s[0:1], s[2:3]
	ds_write_b32 v170, v164 offset:128
	s_or_b64 exec, exec, s[0:1]
	s_waitcnt lgkmcnt(0)
	ds_read_b128 v[146:149], v158 offset:224
	ds_read_b128 v[150:153], v158 offset:192
	ds_read_b128 v[154:157], v158 offset:160
	ds_read_b128 v[216:219], v158 offset:128
	s_waitcnt lgkmcnt(0)
	v_pk_mul_f32 v[16:17], v[16:17], v[148:149]
	v_pk_mul_f32 v[12:13], v[12:13], v[152:153]
	v_pk_mul_f32 v[8:9], v[8:9], v[156:157]
	v_pk_mul_f32 v[4:5], v[4:5], v[218:219]
	v_pk_mul_f32 v[14:15], v[14:15], v[146:147]
	v_pk_mul_f32 v[10:11], v[10:11], v[150:151]
	v_pk_mul_f32 v[6:7], v[6:7], v[154:155]
	v_pk_mul_f32 v[2:3], v[2:3], v[216:217]
	v_pk_mul_f32 v[64:65], v[64:65], v[148:149]
	v_pk_mul_f32 v[60:61], v[60:61], v[152:153]
	v_pk_mul_f32 v[56:57], v[56:57], v[156:157]
	v_pk_mul_f32 v[52:53], v[52:53], v[218:219]
	v_pk_mul_f32 v[62:63], v[62:63], v[146:147]
	v_pk_mul_f32 v[58:59], v[58:59], v[150:151]
	v_pk_mul_f32 v[54:55], v[54:55], v[154:155]
	v_pk_mul_f32 v[50:51], v[50:51], v[216:217]
	v_pk_mul_f32 v[48:49], v[48:49], v[148:149]
	v_pk_mul_f32 v[44:45], v[44:45], v[152:153]
	v_pk_mul_f32 v[40:41], v[40:41], v[156:157]
	v_pk_mul_f32 v[36:37], v[36:37], v[218:219]
	v_pk_mul_f32 v[46:47], v[46:47], v[146:147]
	v_pk_mul_f32 v[42:43], v[42:43], v[150:151]
	v_pk_mul_f32 v[38:39], v[38:39], v[154:155]
	v_pk_mul_f32 v[34:35], v[34:35], v[216:217]
	v_pk_mul_f32 v[32:33], v[32:33], v[148:149]
	v_pk_mul_f32 v[28:29], v[28:29], v[152:153]
	v_pk_mul_f32 v[24:25], v[24:25], v[156:157]
	v_pk_mul_f32 v[20:21], v[20:21], v[218:219]
	v_pk_mul_f32 v[30:31], v[30:31], v[146:147]
	v_pk_mul_f32 v[26:27], v[26:27], v[150:151]
	v_pk_mul_f32 v[22:23], v[22:23], v[154:155]
	v_pk_mul_f32 v[18:19], v[18:19], v[216:217]

.LBB0_549:
	v_cndmask_b32_e64 v165, v165, v202, s[4:5]
	v_mul_f32_e32 v154, 0xbdd53b94, v165
	v_fmamk_f32 v202, v69, 0x3dd53b94, v154
	v_fmamk_f32 v215, v70, 0x3dd53b94, v154
	v_fmamk_f32 v155, v66, 0x3dd53b94, v154
	v_fmamk_f32 v156, v67, 0x3dd53b94, v154
	v_fmamk_f32 v157, v68, 0x3dd53b94, v154
	v_fmamk_f32 v216, v71, 0x3dd53b94, v154
	v_fmamk_f32 v217, v72, 0x3dd53b94, v154
	v_fmamk_f32 v218, v73, 0x3dd53b94, v154
	ds_read_b128 v[66:69], v174 offset:32768
	ds_read_b128 v[70:73], v174 offset:40960
	ds_read_b128 v[146:149], v176 offset:32768
	ds_read_b128 v[150:153], v176 offset:40960
	v_fmamk_f32 v224, v82, 0x3dd53b94, v154
	v_fmamk_f32 v225, v83, 0x3dd53b94, v154
	v_fmamk_f32 v226, v84, 0x3dd53b94, v154
	v_fmamk_f32 v227, v85, 0x3dd53b94, v154
	v_fmamk_f32 v228, v86, 0x3dd53b94, v154
	v_fmamk_f32 v229, v87, 0x3dd53b94, v154
	v_fmamk_f32 v230, v88, 0x3dd53b94, v154
	v_fmamk_f32 v231, v89, 0x3dd53b94, v154
	v_fmamk_f32 v234, v90, 0x3dd53b94, v154
	v_fmamk_f32 v235, v91, 0x3dd53b94, v154
	v_fmamk_f32 v236, v92, 0x3dd53b94, v154
	v_fmamk_f32 v237, v93, 0x3dd53b94, v154
	v_fmamk_f32 v238, v94, 0x3dd53b94, v154
	v_fmamk_f32 v239, v95, 0x3dd53b94, v154
	v_fmamk_f32 v240, v96, 0x3dd53b94, v154
	v_fmamk_f32 v241, v97, 0x3dd53b94, v154
	s_waitcnt lgkmcnt(0)
	v_mfma_f32_32x32x16_bf16 v[82:97], v[66:69], v[142:145], 0
	s_cmp_lg_u32 s98, 0
	s_cbranch_scc1 .Lattn_mla_nopf
	s_add_u32 s0, s38, s20
	s_addc_u32 s1, s39, s21
	s_add_u32 s100, s0, s42
	s_addc_u32 s101, s1, s43
	s_mov_b32 m0, s93
	v_lshl_add_u64 v[254:255], v[246:247], 0, s[100:101]
	global_load_lds_dwordx4 v[254:255], off
	s_add_u32 s100, s0, s46
	s_addc_u32 s101, s1, s47
	s_mov_b32 m0, s94
	v_lshl_add_u64 v[254:255], v[246:247], 0, s[100:101]
	global_load_lds_dwordx4 v[254:255], off
	s_add_u32 s100, s0, s44
	s_addc_u32 s101, s1, s45
	s_add_i32 s98, s89, s24
	s_mov_b32 m0, s98
	v_lshl_add_u64 v[254:255], v[248:249], 0, s[100:101]
	global_load_lds_dwordx4 v[254:255], off
	s_add_u32 s100, s0, s50
	s_addc_u32 s101, s1, s51
	s_add_i32 m0, s98, 0x2000
	v_lshl_add_u64 v[254:255], v[248:249], 0, s[100:101]
	global_load_lds_dwordx4 v[254:255], off
	s_add_u32 s0, s38, s88
	s_addc_u32 s1, s39, s87
	s_add_u32 s0, s0, s58
	s_addc_u32 s1, s1, s59
	s_mov_b32 m0, s95
	v_lshl_add_u64 v[254:255], v[250:251], 0, s[0:1]
	global_load_lds_dwordx4 v[254:255], off
.Lattn_mla_nopf:
	v_fmamk_f32 v232, v79, 0x3dd53b94, v154
	v_fmamk_f32 v233, v80, 0x3dd53b94, v154
	v_fmamk_f32 v219, v74, 0x3dd53b94, v154
	v_fmamk_f32 v220, v75, 0x3dd53b94, v154
	v_fmamk_f32 v221, v76, 0x3dd53b94, v154
	v_fmamk_f32 v222, v77, 0x3dd53b94, v154
	v_fmamk_f32 v223, v78, 0x3dd53b94, v154
	v_fmac_f32_e32 v154, 0x3dd53b94, v81
	v_mfma_f32_32x32x16_bf16 v[66:81], v[70:73], v[142:145], 0
	v_exp_f32_e32 v224, v224
	v_exp_f32_e32 v225, v225
	v_exp_f32_e32 v226, v226
	v_add_f32_e32 v245, 0, v224
	v_add_f32_e32 v245, v225, v245
	v_add_f32_e32 v245, v226, v245
	v_mfma_f32_32x32x16_bf16 v[82:97], v[146:149], v[138:141], v[82:97]
	v_exp_f32_e32 v227, v227
	v_exp_f32_e32 v228, v228
	v_add_f32_e32 v245, v227, v245
	v_add_f32_e32 v245, v228, v245
	v_mfma_f32_32x32x16_bf16 v[66:81], v[150:153], v[138:141], v[66:81]
	ds_read_b128 v[146:149], v178 offset:32768
	ds_read_b128 v[150:153], v178 offset:40960
	v_exp_f32_e32 v229, v229
	v_exp_f32_e32 v230, v230
	v_add_f32_e32 v245, v229, v245
	v_add_f32_e32 v245, v230, v245
	s_waitcnt lgkmcnt(0)
	v_mfma_f32_32x32x16_bf16 v[82:97], v[146:149], v[134:137], v[82:97]
	v_mfma_f32_32x32x16_bf16 v[66:81], v[150:153], v[134:137], v[66:81]
	ds_read_b128 v[146:149], v180 offset:32768
	ds_read_b128 v[150:153], v180 offset:40960
	v_exp_f32_e32 v231, v231
	v_exp_f32_e32 v234, v234
	v_exp_f32_e32 v235, v235
	v_add_f32_e32 v245, v231, v245
	v_add_f32_e32 v245, v234, v245
	v_add_f32_e32 v245, v235, v245
	s_waitcnt lgkmcnt(0)
	v_mfma_f32_32x32x16_bf16 v[82:97], v[146:149], v[130:133], v[82:97]
	v_mfma_f32_32x32x16_bf16 v[66:81], v[150:153], v[130:133], v[66:81]
	ds_read_b128 v[146:149], v182 offset:32768
	ds_read_b128 v[150:153], v182 offset:40960
	v_exp_f32_e32 v236, v236
	v_exp_f32_e32 v237, v237
	v_exp_f32_e32 v238, v238
	v_add_f32_e32 v245, v236, v245
	v_add_f32_e32 v245, v237, v245
	v_add_f32_e32 v245, v238, v245
	s_waitcnt lgkmcnt(0)
	v_mfma_f32_32x32x16_bf16 v[82:97], v[146:149], v[126:129], v[82:97]
	v_mfma_f32_32x32x16_bf16 v[66:81], v[150:153], v[126:129], v[66:81]
	ds_read_b128 v[146:149], v186 offset:32768
	ds_read_b128 v[150:153], v186 offset:40960
	v_exp_f32_e32 v239, v239
	v_exp_f32_e32 v240, v240
	v_exp_f32_e32 v241, v241
	v_add_f32_e32 v245, v239, v245
	v_add_f32_e32 v245, v240, v245
	v_add_f32_e32 v245, v241, v245
	s_waitcnt lgkmcnt(0)
	v_mfma_f32_32x32x16_bf16 v[82:97], v[146:149], v[122:125], v[82:97]
	v_mfma_f32_32x32x16_bf16 v[66:81], v[150:153], v[122:125], v[66:81]
	ds_read_b128 v[146:149], v188 offset:32768
	ds_read_b128 v[150:153], v188 offset:40960
	v_exp_f32_e32 v155, v155
	v_exp_f32_e32 v156, v156
	v_exp_f32_e32 v157, v157
	v_add_f32_e32 v245, v155, v245
	v_add_f32_e32 v245, v156, v245
	v_add_f32_e32 v245, v157, v245
	s_waitcnt lgkmcnt(0)
	v_mfma_f32_32x32x16_bf16 v[82:97], v[146:149], v[118:121], v[82:97]
	v_mfma_f32_32x32x16_bf16 v[66:81], v[150:153], v[118:121], v[66:81]
	ds_read_b128 v[146:149], v190 offset:32768
	ds_read_b128 v[150:153], v190 offset:40960
	v_exp_f32_e32 v202, v202
	v_exp_f32_e32 v215, v215
	v_exp_f32_e32 v216, v216
	v_add_f32_e32 v245, v202, v245
	v_add_f32_e32 v245, v215, v245
	v_add_f32_e32 v245, v216, v245
	s_waitcnt lgkmcnt(0)
	v_mfma_f32_32x32x16_bf16 v[82:97], v[146:149], v[114:117], v[82:97]
	v_mfma_f32_32x32x16_bf16 v[66:81], v[150:153], v[114:117], v[66:81]
	ds_read_b128 v[146:149], v192
	ds_read_b128 v[150:153], v192 offset:4096
	v_exp_f32_e32 v217, v217
	v_exp_f32_e32 v218, v218
	v_exp_f32_e32 v219, v219
	v_add_f32_e32 v245, v217, v245
	v_add_f32_e32 v245, v218, v245
	v_add_f32_e32 v245, v219, v245
	s_waitcnt lgkmcnt(0)
	v_mfma_f32_32x32x16_bf16 v[82:97], v[146:149], v[110:113], v[82:97]
	v_mfma_f32_32x32x16_bf16 v[66:81], v[150:153], v[110:113], v[66:81]
	ds_read_b128 v[146:149], v194
	ds_read_b128 v[150:153], v194 offset:4096
	v_exp_f32_e32 v220, v220
	v_exp_f32_e32 v221, v221
	v_exp_f32_e32 v222, v222
	v_add_f32_e32 v245, v220, v245
	v_add_f32_e32 v245, v221, v245
	v_add_f32_e32 v245, v222, v245
	s_waitcnt lgkmcnt(0)
	v_mfma_f32_32x32x16_bf16 v[82:97], v[146:149], v[106:109], v[82:97]
	v_mfma_f32_32x32x16_bf16 v[66:81], v[150:153], v[106:109], v[66:81]
	ds_read_b128 v[146:149], v196
	ds_read_b128 v[150:153], v196 offset:4096
	v_exp_f32_e32 v223, v223
	v_exp_f32_e32 v242, v232
	v_exp_f32_e32 v243, v233
	v_add_f32_e32 v245, v223, v245
	v_add_f32_e32 v245, v242, v245
	v_add_f32_e32 v245, v243, v245
	s_waitcnt lgkmcnt(0)
	v_mfma_f32_32x32x16_bf16 v[82:97], v[146:149], v[102:105], v[82:97]
	v_mfma_f32_32x32x16_bf16 v[66:81], v[150:153], v[102:105], v[66:81]
	ds_read_b128 v[146:149], v199
	ds_read_b128 v[150:153], v199 offset:4096
	v_lshl_add_u32 v214, s23, 14, v200
	ds_read_b64_tr_b16 v[206:207], v214 offset:0
	ds_read_b64_tr_b16 v[208:209], v214 offset:0x800
	ds_read_b64_tr_b16 v[210:211], v214 offset:0x1000
	ds_read_b64_tr_b16 v[212:213], v214 offset:0x1800
	v_exp_f32_e32 v244, v154
	s_waitcnt lgkmcnt(4)
	v_mfma_f32_32x32x16_bf16 v[82:97], v[146:149], v[98:101], v[82:97]
	v_mfma_f32_32x32x16_bf16 v[66:81], v[150:153], v[98:101], v[66:81]
	v_add_f32_e32 v232, v244, v245
	v_mov_b32_e32 v233, v232
	s_nop 1
	v_permlane32_swap_b32_e32 v232, v233
	v_cvt_pk_bf16_f32 v146, v224, v225
	v_cvt_pk_bf16_f32 v147, v226, v227
	v_cvt_pk_bf16_f32 v148, v228, v229
	v_cvt_pk_bf16_f32 v149, v230, v231
	v_cvt_pk_bf16_f32 v150, v234, v235
	v_cvt_pk_bf16_f32 v151, v236, v237
	v_cvt_pk_bf16_f32 v152, v238, v239
	v_cvt_pk_bf16_f32 v153, v240, v241
	v_cvt_pk_bf16_f32 v154, v155, v156
	v_cvt_pk_bf16_f32 v155, v157, v202
	v_cvt_pk_bf16_f32 v156, v215, v216
	v_cvt_pk_bf16_f32 v157, v217, v218
	v_cvt_pk_bf16_f32 v216, v219, v220
	v_cvt_pk_bf16_f32 v217, v221, v222
	v_cvt_pk_bf16_f32 v218, v223, v242
	v_cvt_pk_bf16_f32 v219, v243, v244
	s_nop 0
	v_permlane32_swap_b32_e32 v146, v148
	v_permlane32_swap_b32_e32 v147, v149
	v_permlane32_swap_b32_e32 v150, v152
	v_permlane32_swap_b32_e32 v151, v153
	v_permlane32_swap_b32_e32 v154, v156
	v_permlane32_swap_b32_e32 v155, v157
	v_permlane32_swap_b32_e32 v216, v218
	v_permlane32_swap_b32_e32 v217, v219
	ds_read_b64_tr_b16 v[228:229], v214 offset:0x2000
	ds_read_b64_tr_b16 v[230:231], v214 offset:0x2800
	ds_read_b64_tr_b16 v[234:235], v214 offset:0x3000
	ds_read_b64_tr_b16 v[236:237], v214 offset:0x3800
	s_nop 0
	s_waitcnt lgkmcnt(6)
	v_mfma_f32_32x32x16_bf16 v[2:17], v[146:149], v[206:209], v[2:17]
	ds_read_b64_tr_b16 v[220:221], v214 offset:0x200
	ds_read_b64_tr_b16 v[222:223], v214 offset:0xa00
	v_max_f32_e32 v202, v83, v83
	v_max_f32_e32 v215, v82, v82
	v_max_f32_e32 v202, v215, v202
	v_max3_f32 v202, v202, v84, v85
	v_max3_f32 v202, v202, v86, v87
	s_waitcnt lgkmcnt(6)
	v_mfma_f32_32x32x16_bf16 v[2:17], v[150:153], v[210:213], v[2:17]
	ds_read_b64_tr_b16 v[224:225], v214 offset:0x1200
	ds_read_b64_tr_b16 v[226:227], v214 offset:0x1a00
	v_max3_f32 v202, v202, v88, v89
	v_max3_f32 v202, v202, v90, v91
	v_max3_f32 v202, v202, v92, v93
	v_max3_f32 v202, v202, v94, v95
	v_max3_f32 v202, v202, v96, v97
	s_waitcnt lgkmcnt(6)
	v_mfma_f32_32x32x16_bf16 v[2:17], v[154:157], v[228:231], v[2:17]
	ds_read_b64_tr_b16 v[228:229], v214 offset:0x2200
	ds_read_b64_tr_b16 v[230:231], v214 offset:0x2a00
	ds_read_b64_tr_b16 v[238:239], v214 offset:0x3200
	ds_read_b64_tr_b16 v[240:241], v214 offset:0x3a00
	s_waitcnt lgkmcnt(8)
	v_mfma_f32_32x32x16_bf16 v[2:17], v[216:219], v[234:237], v[2:17]
	s_waitcnt lgkmcnt(6)
	v_mfma_f32_32x32x16_bf16 v[50:65], v[146:149], v[220:223], v[50:65]
	v_max3_f32 v202, v202, v66, v67
	v_max3_f32 v202, v202, v68, v69
	v_max3_f32 v202, v202, v70, v71
	v_max3_f32 v202, v202, v72, v73
	v_max3_f32 v202, v202, v74, v75
	v_max3_f32 v202, v202, v76, v77
	v_max3_f32 v202, v202, v78, v79
	s_waitcnt lgkmcnt(4)
	v_mfma_f32_32x32x16_bf16 v[50:65], v[150:153], v[224:227], v[50:65]
	v_max3_f32 v202, v202, v80, v81
	v_mov_b32_e32 v215, v202
	s_nop 1
	v_permlane32_swap_b32_e32 v202, v215
	v_max_f32_e32 v215, v215, v215
	v_max_f32_e32 v202, v202, v202
	v_max_f32_e32 v202, v202, v215
	v_max_f32_e32 v220, v165, v165
	v_sub_f32_e32 v215, v202, v165
	v_max_f32_e32 v202, v220, v202
	v_sub_f32_e32 v220, v165, v202
	v_mul_f32_e32 v220, 0x3dd53b94, v220
	s_waitcnt lgkmcnt(2)
	v_mfma_f32_32x32x16_bf16 v[50:65], v[154:157], v[228:231], v[50:65]
	v_exp_f32_e32 v220, v220
	v_cmp_ge_f32_e32 vcc, s77, v215
	s_cmp_eq_u64 vcc, exec
	s_cselect_b64 s[4:5], -1, 0
	v_cndmask_b32_e64 v215, v220, 1.0, s[4:5]
	ds_read_b64_tr_b16 v[220:221], v214 offset:0x400
	ds_read_b64_tr_b16 v[222:223], v214 offset:0xc00
	ds_read_b64_tr_b16 v[224:225], v214 offset:0x1400
	s_waitcnt lgkmcnt(3)
	v_mfma_f32_32x32x16_bf16 v[50:65], v[216:219], v[238:241], v[50:65]
	ds_read_b64_tr_b16 v[226:227], v214 offset:0x1c00
	ds_read_b64_tr_b16 v[228:229], v214 offset:0x2400
	ds_read_b64_tr_b16 v[230:231], v214 offset:0x2c00
	ds_read_b64_tr_b16 v[234:235], v214 offset:0x3400
	ds_read_b64_tr_b16 v[236:237], v214 offset:0x3c00
	s_waitcnt lgkmcnt(6)
	v_mfma_f32_32x32x16_bf16 v[34:49], v[146:149], v[220:223], v[34:49]
	ds_read_b64_tr_b16 v[220:221], v214 offset:0x600
	ds_read_b64_tr_b16 v[222:223], v214 offset:0xe00
	s_waitcnt lgkmcnt(6)
	v_mfma_f32_32x32x16_bf16 v[34:49], v[150:153], v[224:227], v[34:49]
	ds_read_b64_tr_b16 v[224:225], v214 offset:0x1600
	ds_read_b64_tr_b16 v[226:227], v214 offset:0x1e00
	s_waitcnt lgkmcnt(6)
	v_mfma_f32_32x32x16_bf16 v[34:49], v[154:157], v[228:231], v[34:49]
	ds_read_b64_tr_b16 v[228:229], v214 offset:0x2600
	ds_read_b64_tr_b16 v[230:231], v214 offset:0x2e00
	ds_read_b64_tr_b16 v[238:239], v214 offset:0x3600
	ds_read_b64_tr_b16 v[240:241], v214 offset:0x3e00
	s_waitcnt lgkmcnt(8)
	v_mfma_f32_32x32x16_bf16 v[34:49], v[216:219], v[234:237], v[34:49]
	s_waitcnt lgkmcnt(6)
	v_mfma_f32_32x32x16_bf16 v[18:33], v[146:149], v[220:223], v[18:33]
	v_cmp_gt_f32_e32 vcc, 1.0, v215
	s_waitcnt lgkmcnt(4)
	v_mfma_f32_32x32x16_bf16 v[18:33], v[150:153], v[224:227], v[18:33]
	s_waitcnt lgkmcnt(2)
	v_mfma_f32_32x32x16_bf16 v[18:33], v[154:157], v[228:231], v[18:33]
	s_waitcnt lgkmcnt(0)
	v_mfma_f32_32x32x16_bf16 v[18:33], v[216:219], v[238:241], v[18:33]
	s_cbranch_vccz .LBB0_553
	s_and_saveexec_b64 s[0:1], s[2:3]
	ds_write_b32 v170, v215 offset:128
	s_or_b64 exec, exec, s[0:1]
	s_waitcnt lgkmcnt(0)
	ds_read_b128 v[146:149], v158 offset:224
	ds_read_b128 v[150:153], v158 offset:192
	ds_read_b128 v[154:157], v158 offset:160
	ds_read_b128 v[216:219], v158 offset:128
	s_waitcnt lgkmcnt(0)
	v_pk_mul_f32 v[16:17], v[16:17], v[148:149]
	v_pk_mul_f32 v[12:13], v[12:13], v[152:153]
	v_pk_mul_f32 v[8:9], v[8:9], v[156:157]
	v_pk_mul_f32 v[4:5], v[4:5], v[218:219]
	v_pk_mul_f32 v[14:15], v[14:15], v[146:147]
	v_pk_mul_f32 v[10:11], v[10:11], v[150:151]
	v_pk_mul_f32 v[6:7], v[6:7], v[154:155]
	v_pk_mul_f32 v[2:3], v[2:3], v[216:217]
	v_pk_mul_f32 v[64:65], v[64:65], v[148:149]
	v_pk_mul_f32 v[60:61], v[60:61], v[152:153]
	v_pk_mul_f32 v[56:57], v[56:57], v[156:157]
	v_pk_mul_f32 v[52:53], v[52:53], v[218:219]
	v_pk_mul_f32 v[62:63], v[62:63], v[146:147]
	v_pk_mul_f32 v[58:59], v[58:59], v[150:151]
	v_pk_mul_f32 v[54:55], v[54:55], v[154:155]
	v_pk_mul_f32 v[50:51], v[50:51], v[216:217]
	v_pk_mul_f32 v[48:49], v[48:49], v[148:149]
	v_pk_mul_f32 v[44:45], v[44:45], v[152:153]
	v_pk_mul_f32 v[40:41], v[40:41], v[156:157]
	v_pk_mul_f32 v[36:37], v[36:37], v[218:219]
	v_pk_mul_f32 v[46:47], v[46:47], v[146:147]
	v_pk_mul_f32 v[42:43], v[42:43], v[150:151]
	v_pk_mul_f32 v[38:39], v[38:39], v[154:155]
	v_pk_mul_f32 v[34:35], v[34:35], v[216:217]
	v_pk_mul_f32 v[32:33], v[32:33], v[148:149]
	v_pk_mul_f32 v[28:29], v[28:29], v[152:153]
	v_pk_mul_f32 v[24:25], v[24:25], v[156:157]
	v_pk_mul_f32 v[20:21], v[20:21], v[218:219]
	v_pk_mul_f32 v[30:31], v[30:31], v[146:147]
	v_pk_mul_f32 v[26:27], v[26:27], v[150:151]
	v_pk_mul_f32 v[22:23], v[22:23], v[154:155]
	v_pk_mul_f32 v[18:19], v[18:19], v[216:217]
